# sub-phase 2: workgroups 256-263 (presumed CU partners of the chain workgroups 0-7) skip the work queue so the long dn_scan chains get their CU alone
# speedup vs baseline: 1.0017x; 1.0017x over previous
; __device__ __forceinline__ void run_phase(const P& pp, int ph, char* smem, int* s_item) {
;     ...
;   while (true) {
;     if (threadIdx.x == 0) *s_item = atomicAdd(ctr, 1);
;     __syncthreads();
;     const int it = *s_item;
;     __syncthreads();
;     if (it >= total) break;
.Lq_partner:
	s_sub_u32 vcc_hi, vcc_hi, 1024
	s_cmp_lt_u32 vcc_hi, 32
	s_cbranch_scc0 .Lq_atomic8
	v_mov_b32_e32 v1, 0x10000
	s_branch .Lq_done
